# ph10: blocks < 256 (two attention units) run at s_setprio 1 so the co-resident one-unit block fills the gaps
# baseline (speedup 1.0000x reference)
.LBB0_1060:
	s_cmp_gt_i32 s22, 10
	s_cselect_b64 s[4:5], -1, 0
	s_cmp_lt_i32 s23, 11
	s_cselect_b64 s[6:7], -1, 0
	s_or_b64 s[4:5], s[4:5], s[6:7]
	s_and_b64 vcc, exec, s[4:5]
	s_cbranch_vccnz .LBB0_1130
	s_cmpk_gt_i32 s2, 0x2ff
	v_and_b32_e32 v147, 0x3ff, v0
	s_cbranch_scc1 .LBB0_1077
	s_cmpk_lt_u32 s2, 0x100
	s_cbranch_scc0 .Lph10_noprio
	s_setprio 1
.Lph10_noprio:
	s_waitcnt vmcnt(0)
	v_lshrrev_b32_e32 v2, 1, v147
	v_and_b32_e32 v151, 0x1e0, v2
	v_lshrrev_b32_e32 v2, 4, v147
	v_xor_b32_e32 v6, v2, v147
	v_lshlrev_b32_e32 v7, 3, v6
	v_and_b32_e32 v6, 0x78, v7
	v_and_b32_e32 v8, 56, v7
	v_lshlrev_b32_e32 v7, 4, v147
	s_load_dwordx8 s[4:11], s[0:1], 0x140
	v_lshrrev_b32_e32 v5, 5, v147
	v_and_b32_e32 v177, 0x3c00, v7
	v_and_b32_e32 v7, 15, v147
	v_bfe_u32 v175, v147, 5, 1
	v_bitop3_b32 v9, v5, v7, 1 bitop3:0x6c
	v_lshrrev_b32_e32 v176, 3, v147
	v_lshlrev_b32_e32 v180, 4, v9
	v_bitop3_b32 v9, v175, v7, 2 bitop3:0x36
	v_lshlrev_b32_e32 v4, 10, v2
	v_mov_b32_e32 v3, 0
	v_lshlrev_b32_e32 v2, 7, v176
	v_bfe_u32 v178, v147, 1, 3
	v_lshlrev_b32_e32 v181, 4, v9
	v_bitop3_b32 v9, v175, v7, 4 bitop3:0x36
	v_lshlrev_b32_e32 v182, 4, v9
	v_bitop3_b32 v9, v175, v7, 6 bitop3:0x36
	v_bitop3_b32 v5, v5, v178, 1 bitop3:0x6c
	s_load_dwordx2 s[14:15], s[0:1], 0x98
	s_load_dwordx2 s[16:17], s[0:1], 0x128
	s_waitcnt lgkmcnt(0)
	v_lshl_add_u64 v[14:15], s[4:5], 0, v[2:3]
	v_lshlrev_b32_e32 v2, 1, v8
	v_lshlrev_b32_e32 v183, 4, v9
	v_bitop3_b32 v9, v175, v7, 8 bitop3:0x36
	v_lshlrev_b32_e32 v188, 4, v5
	v_bitop3_b32 v5, v175, v178, 2 bitop3:0x36
	v_lshl_add_u64 v[152:153], v[14:15], 0, v[2:3]
	v_mbcnt_lo_u32_b32 v2, -1, 0
	v_lshlrev_b32_e32 v184, 4, v9
	v_bitop3_b32 v9, v175, v7, 10 bitop3:0x36
	v_lshlrev_b32_e32 v189, 4, v5
	v_bitop3_b32 v5, v175, v178, 4 bitop3:0x36
	v_mbcnt_hi_u32_b32 v201, -1, v2
	v_and_b32_e32 v149, 31, v147
	v_lshlrev_b32_e32 v10, 3, v175
	v_lshlrev_b32_e32 v185, 4, v9
	v_bitop3_b32 v9, v175, v7, 12 bitop3:0x36
	v_bitop3_b32 v7, v175, v7, 14 bitop3:0x36
	v_lshlrev_b32_e32 v190, 4, v5
	v_bitop3_b32 v5, v175, v178, 6 bitop3:0x36
	v_lshlrev_b32_e32 v12, 2, v175
	s_add_u32 s12, s0, 0x468
	v_and_b32_e32 v2, 64, v201
	v_or_b32_e32 v174, 0x1000, v151
	v_lshlrev_b32_e32 v179, 7, v149
	v_lshlrev_b32_e32 v186, 4, v9
	v_lshlrev_b32_e32 v187, 4, v7
	v_lshlrev_b32_e32 v191, 4, v5
	s_addc_u32 s13, s1, 0
	s_mov_b32 s5, 0
	s_movk_i32 s3, 0xc00
	v_mov_b64_e32 v[154:155], s[6:7]
	v_lshlrev_b32_e32 v156, 1, v10
	v_mov_b32_e32 v157, v3
	v_lshlrev_b32_e32 v158, 1, v4
	v_mov_b32_e32 v159, v3
	v_lshlrev_b32_e32 v160, 1, v8
	v_mov_b32_e32 v161, v3
	v_lshlrev_b32_e32 v162, 1, v6
	v_mov_b32_e32 v163, v3
	s_mov_b64 s[6:7], 0x8000
	v_add_u32_e32 v192, 0x1000, v177
	s_mov_b64 s[18:19], 0x10000
	v_add_u32_e32 v193, 0x2000, v177
	s_mov_b64 s[24:25], 0x18000
	v_add_u32_e32 v194, 0x3000, v177
	v_or_b32_e32 v195, 0x4000, v177
	s_mov_b64 s[26:27], 0x1000
	v_add_u32_e32 v196, 0x5000, v177
	v_add_u32_e32 v197, 0x6000, v177
	v_add_u32_e32 v198, 0x7000, v177
	v_or_b32_e32 v199, 0x8000, v177
	v_add_u32_e32 v200, 0x9000, v177
	s_mov_b64 s[28:29], 0x80
	v_lshlrev_b32_e32 v164, 1, v12
	v_xor_b32_e32 v202, 32, v201
	v_add_u32_e32 v203, 64, v2
	s_mov_b32 s42, s2
	s_branch .LBB0_1064

.LBB0_1077:
	s_setprio 0
	s_cmp_lt_i32 s23, 12
	s_cbranch_scc1 .LBB0_1130
	s_waitcnt vmcnt(0)
	v_cmp_eq_u32_e32 vcc, 0, v147
	s_waitcnt vmcnt(0)
	v_mov_b32_e32 v2, v146
	v_mov_b32_e32 v4, v148
	s_waitcnt lgkmcnt(0)
	s_barrier
	s_and_saveexec_b64 s[4:5], vcc
	s_cbranch_execz .LBB0_1127
	v_cmp_eq_u32_e32 vcc, 0, v148
	v_mov_b32_e32 v2, v146
	v_mov_b32_e32 v4, v148
	s_waitcnt vmcnt(0) expcnt(0) lgkmcnt(0)
	s_and_saveexec_b64 s[6:7], vcc
	s_cbranch_execz .LBB0_1094
	s_load_dwordx2 s[12:13], s[0:1], 0x468
	s_load_dword s3, s[0:1], 0x470
	s_add_u32 s8, s20, 0x1000
	s_addc_u32 s9, s21, 0
	s_add_u32 s10, s20, 0x1100
	s_waitcnt lgkmcnt(0)
	s_mul_i32 s11, s13, s12
	s_mul_i32 s3, s11, s3
	s_addc_u32 s11, s21, 0
	s_add_u32 s12, s20, 0x1200
	s_addc_u32 s13, s21, 0
	s_add_u32 s14, s20, 0x1300
	s_addc_u32 s15, s21, 0
	s_mov_b32 s26, 1
	v_mov_b32_e32 v18, 0
	s_branch .LBB0_1082
